# waves 4-7: LDS-DMA issue spread over the MFMAs after their barrier (every 4th)
# speedup vs baseline: 1.0206x; 1.0133x over previous
; DI void lds_barrier() { asm volatile("s_waitcnt lgkmcnt(0)\n\ts_barrier" ::: "memory"); }
; #define ISSUE() do { const int ka_ = (kp + koff >= nk) ? kp + koff - nk : kp + koff; \
;                 glds16x5(A + ka_ * 32, pbt + (size_t)(ka_ >> 1) * 16384 + (ka_ & 1) * 32, va, vb0, vb1, vb2, vb3, lbase + (unsigned)sp * H5_STAGE); \
;                 ++kp; if (kp == nk) { kp = 0; ++tp; pbt += (size_t)512 * K; if (tp == ntw) { tp = 0; pbt = Bt; } } sp = (sp == 2) ? 0 : sp + 1; } while (0)
; DI void run_jobs(const Params& P, int rb, int jj_lo, int jj_hi, unsigned char* smem) {
;     ...
;             ISSUE();
;             ISSUE();
;             ISSUE();
;             asm volatile("s_waitcnt vmcnt(10)" ::: "memory");
;             lds_barrier();
;             int kt = 0, t = toff, st = 0;
;             for (int s = 0; s < S; ++s) {
;                 const unsigned char* sc_ = smem + st * H5_STAGE;
;                 bf16x8 af[4], bfr[8];
; #pragma unroll
;                 for (int mt = 0; mt < 4; ++mt) af[mt] = *(const bf16x8*)(sc_ + fa + mt * 1024);
; #pragma unroll
;                 for (int n_ = 0; n_ < 8; ++n_) bfr[n_] = *(const bf16x8*)(sc_ + fb + n_ * 1024);
;                 if (kt == 0) {
; #pragma unroll
;                     for (int i = 0; i < 4; ++i)
; #pragma unroll
;                         for (int jq = 0; jq < 8; ++jq) acc[i][jq] = (f32x4){0.f, 0.f, 0.f, 0.f};
;                 }
; #pragma unroll
;                 for (int mt = 0; mt < 4; ++mt)
; #pragma unroll
;                     for (int n_ = 0; n_ < 8; ++n_) acc[mt][n_] = __builtin_amdgcn_mfma_f32_16x16x32_bf16(bfr[n_], af[mt], acc[mt][n_], 0, 0, 0);
;                 if (s + 2 < S) asm volatile("s_waitcnt vmcnt(5)" ::: "memory");
;                 else asm volatile("s_waitcnt vmcnt(0)" ::: "memory");
;                 lds_barrier();
;                 if (s + 3 < S) ISSUE();
;                 st = (st == 2) ? 0 : st + 1;
;                 ++kt;
.Lg_y:
	s_nop 0
	s_add_i32 s21, s61, 3
	s_cmp_ge_u32 s21, s54
	s_cbranch_scc1 .Lg_y_plain
	s_add_i32 s8, s53, s57
	s_cmp_ge_i32 s8, s52
	s_cselect_b32 s9, s52, 0
	s_sub_i32 s21, s8, s9
	s_lshl_b32 s8, s21, 5
	s_ashr_i32 s9, s8, 31
	s_lshl_b64 s[8:9], s[8:9], 1
	s_add_u32 s8, s28, s8
	s_addc_u32 s9, s29, s9
	s_ashr_i32 s64, s21, 1
	s_ashr_i32 s65, s64, 31
	s_lshl_b64 s[64:65], s[64:65], 15
	s_add_u32 s63, s4, s64
	s_addc_u32 s65, s58, s65
	s_lshl_b32 s21, s21, 14
	s_and_b32 s21, s21, 0x4000
	s_add_u32 s64, s63, s21
	s_mul_i32 s21, s23, 0xa000
	s_addc_u32 s65, s65, 0
	s_add_i32 s21, s21, s55
	s_mov_b32 m0, s21
	s_waitcnt lgkmcnt(10)
	v_mfma_f32_16x16x32_bf16 v[124:127], v[140:143], v[172:175], v[124:127]
	s_waitcnt lgkmcnt(9)
	v_mfma_f32_16x16x32_bf16 v[120:123], v[144:147], v[172:175], v[120:123]
	s_waitcnt lgkmcnt(8)
	v_mfma_f32_16x16x32_bf16 v[116:119], v[148:151], v[172:175], v[116:119]
	s_waitcnt lgkmcnt(7)
	v_mfma_f32_16x16x32_bf16 v[112:115], v[152:155], v[172:175], v[112:115]
	s_waitcnt lgkmcnt(6)
	v_mfma_f32_16x16x32_bf16 v[108:111], v[156:159], v[172:175], v[108:111]
	s_waitcnt lgkmcnt(5)
	v_mfma_f32_16x16x32_bf16 v[104:107], v[160:163], v[172:175], v[104:107]
	s_waitcnt lgkmcnt(4)
	v_mfma_f32_16x16x32_bf16 v[100:103], v[164:167], v[172:175], v[100:103]
	s_waitcnt lgkmcnt(3)
	v_mfma_f32_16x16x32_bf16 v[96:99], v[132:135], v[172:175], v[96:99]
	s_waitcnt lgkmcnt(2)
	v_mfma_f32_16x16x32_bf16 v[92:95], v[140:143], v[168:171], v[92:95]
	v_mfma_f32_16x16x32_bf16 v[88:91], v[144:147], v[168:171], v[88:91]
	v_mfma_f32_16x16x32_bf16 v[84:87], v[148:151], v[168:171], v[84:87]
	v_mfma_f32_16x16x32_bf16 v[80:83], v[152:155], v[168:171], v[80:83]
	s_waitcnt vmcnt(5)
	s_waitcnt lgkmcnt(0)
	s_barrier
	v_mfma_f32_16x16x32_bf16 v[76:79], v[156:159], v[168:171], v[76:79]
	v_mfma_f32_16x16x32_bf16 v[72:75], v[160:163], v[168:171], v[72:75]
	global_load_lds_dwordx4 v239, s[8:9]
	s_add_u32 m0, m0, 0x2000
	v_mfma_f32_16x16x32_bf16 v[68:71], v[164:167], v[168:171], v[68:71]
	v_mfma_f32_16x16x32_bf16 v[64:67], v[132:135], v[168:171], v[64:67]
	s_waitcnt lgkmcnt(1)
	v_mfma_f32_16x16x32_bf16 v[60:63], v[140:143], v[136:139], v[60:63]
	v_mfma_f32_16x16x32_bf16 v[56:59], v[144:147], v[136:139], v[56:59]
	global_load_lds_dwordx4 v237, s[64:65]
	s_add_u32 m0, m0, 0x2000
	v_mfma_f32_16x16x32_bf16 v[52:55], v[148:151], v[136:139], v[52:55]
	v_mfma_f32_16x16x32_bf16 v[48:51], v[152:155], v[136:139], v[48:51]
	v_mfma_f32_16x16x32_bf16 v[44:47], v[156:159], v[136:139], v[44:47]
	v_mfma_f32_16x16x32_bf16 v[40:43], v[160:163], v[136:139], v[40:43]
	global_load_lds_dwordx4 v240, s[64:65]
	s_add_u32 m0, m0, 0x2000
	v_mfma_f32_16x16x32_bf16 v[36:39], v[164:167], v[136:139], v[36:39]
	v_mfma_f32_16x16x32_bf16 v[32:35], v[132:135], v[136:139], v[32:35]
	s_waitcnt lgkmcnt(0)
	v_mfma_f32_16x16x32_bf16 v[28:31], v[140:143], v[128:131], v[28:31]
	v_mfma_f32_16x16x32_bf16 v[24:27], v[144:147], v[128:131], v[24:27]
	global_load_lds_dwordx4 v238, s[64:65]
	s_add_u32 m0, m0, 0x2000
	v_mfma_f32_16x16x32_bf16 v[20:23], v[148:151], v[128:131], v[20:23]
	v_mfma_f32_16x16x32_bf16 v[16:19], v[152:155], v[128:131], v[16:19]
	v_mfma_f32_16x16x32_bf16 v[12:15], v[156:159], v[128:131], v[12:15]
	v_mfma_f32_16x16x32_bf16 v[8:11], v[160:163], v[128:131], v[8:11]
	global_load_lds_dwordx4 v241, s[64:65]
	v_mfma_f32_16x16x32_bf16 v[4:7], v[164:167], v[128:131], v[4:7]
	v_mfma_f32_16x16x32_bf16 v[0:3], v[132:135], v[128:131], v[0:3]
	s_add_i32 s21, s53, 1
	s_cmp_eq_u32 s21, s52
	s_cselect_b64 s[8:9], -1, 0
	s_add_i32 s53, s56, 1
	s_add_u32 s63, s4, s59
	s_addc_u32 s66, s58, 0
	s_cmp_eq_u32 s53, s22
	s_cselect_b64 s[64:65], -1, 0
	s_and_b64 s[64:65], s[64:65], exec
	s_cselect_b32 s63, s94, s63
	s_cselect_b32 s64, s95, s66
	s_cselect_b32 s53, 0, s53
	s_and_b64 s[8:9], s[8:9], exec
	s_cselect_b32 s58, s64, s58
	s_cselect_b32 s4, s63, s4
	s_cselect_b32 s56, s53, s56
	s_cselect_b32 s53, 0, s21
	s_add_i32 s8, s23, 1
	s_cmp_lg_u32 s23, 2
	s_cselect_b32 s23, s8, 0
	s_branch .LBB0_150
